# attention unit prologue: conv-weight loads issued ahead of the barriers that used to precede them, last conv store no longer waited before the main loop (vmcnt 4->5)
# speedup vs baseline: 1.0070x; 1.0070x over previous
.LBB0_418:
	s_ashr_i32 s4, s65, 3
	s_ashr_i32 s5, s4, 31
	s_lshl_b32 s75, s66, 7
	s_lshr_b32 s76, s68, 8
	s_and_b32 s71, s70, 3
	s_lshl_b64 s[40:41], s[4:5], 12
	s_ashr_i32 s38, s75, 31
	s_add_u32 s40, s40, s75
	s_addc_u32 s41, s41, s38
	s_lshl_b32 s38, s71, 5
	s_or_b32 s42, s40, s38
	s_mov_b32 s43, s41
	s_lshl_b32 s38, s65, 7
	s_lshl_b64 s[42:43], s[42:43], 11
	s_and_b32 s38, s38, 0x380
	s_lshl_b32 s50, s76, 6
	s_lshl_b64 s[4:5], s[4:5], 23
	s_add_u32 s44, s3, s4
	s_addc_u32 s45, s58, s5
	s_add_u32 s51, s16, s4
	s_addc_u32 s69, s17, s5
	s_lshl_b32 s74, s70, 10
	s_cmp_lg_u32 0, -1
	s_cselect_b32 s48, 0, 0
	s_add_i32 s72, s74, s48
	s_add_u32 s42, s10, s42
	s_addc_u32 s43, s11, s43
	s_lshl_b32 s38, s38, 1
	s_add_u32 s42, s42, s38
	s_addc_u32 s43, s43, 0
	s_lshl_b32 s48, s76, 7
	s_add_u32 s48, s42, s48
	s_addc_u32 s49, s43, 0
	s_add_u32 s44, s44, s38
	s_addc_u32 s45, s45, 0
	s_add_u32 s42, s51, s38
	s_addc_u32 s43, s69, 0
	s_lshl_b32 s69, s70, 4
	s_lshl_b32 s51, s71, 15
	global_load_dwordx4 v[14:17], v[38:39], off
	s_nop 0
	global_load_dwordx4 v[10:13], v[10:11], off offset:1024
	v_add_u32_e32 v226, s69, v215
	s_add_i32 s51, s51, s50
	s_add_i32 s73, s72, 0x10000
	global_load_dwordx4 v[40:43], v[192:193], off
	global_load_dwordx4 v[44:47], v[192:193], off offset:16
	global_load_dwordx4 v[48:51], v[194:195], off
	global_load_dwordx4 v[52:55], v[194:195], off offset:16
	global_load_dwordx4 v[66:69], v[196:197], off
	global_load_dwordx4 v[70:73], v[196:197], off offset:16
	s_mov_b32 s50, m0
	s_mov_b32 m0, s72
	s_nop 0
	global_load_lds_dwordx4 v226, s[44:45]
	s_mov_b32 m0, s50
	s_add_u32 s50, s44, 0x80
	v_add_u32_e32 v227, s51, v216
	s_addc_u32 s51, s45, 0
	s_add_i32 s77, s72, 0x2000
	s_mov_b32 s78, m0
	s_mov_b32 m0, s77
	s_nop 0
	global_load_lds_dwordx4 v226, s[50:51]
	s_mov_b32 m0, s78
	s_mov_b32 s50, m0
	s_mov_b32 m0, s73
	s_nop 0
	global_load_lds_dwordx4 v227, s[42:43]
	s_mov_b32 m0, s50
	s_add_u32 s50, s42, 0x80
	s_addc_u32 s51, s43, 0
	s_add_i32 s77, s72, 0x12000
	s_mov_b32 s78, m0
	s_mov_b32 m0, s77
	s_nop 0
	global_load_lds_dwordx4 v227, s[50:51]
	s_mov_b32 m0, s78
	s_add_u32 s50, s44, 0x20000
	s_addc_u32 s51, s45, 0
	s_add_i32 s77, s72, 0x4000
	s_mov_b32 s78, m0
	s_mov_b32 m0, s77
	s_nop 0
	global_load_lds_dwordx4 v226, s[50:51]
	s_mov_b32 m0, s78
	s_add_u32 s50, s44, 0x20080
	s_addc_u32 s51, s45, 0
	s_add_i32 s77, s72, 0x6000
	s_mov_b32 s78, m0
	s_mov_b32 m0, s77
	s_nop 0
	global_load_lds_dwordx4 v226, s[50:51]
	s_mov_b32 m0, s78
	v_lshlrev_b32_e32 v0, 1, v219
	global_load_dwordx4 v[120:123], v0, s[48:49]
	global_load_dwordx4 v[116:119], v0, s[48:49] offset:32
	global_load_dwordx4 v[112:115], v0, s[48:49] offset:64
	global_load_dwordx4 v[108:111], v0, s[48:49] offset:96
	s_add_u32 s48, s44, 0x40000
	s_addc_u32 s49, s45, 0
	s_add_i32 s50, s72, 0x8000
	s_mov_b32 s51, m0
	s_mov_b32 m0, s50
	s_nop 0
	global_load_lds_dwordx4 v226, s[48:49]
	s_mov_b32 m0, s51
	s_add_u32 s48, s44, 0x40080
	s_addc_u32 s49, s45, 0
	s_add_i32 s50, s72, 0xa000
	s_mov_b32 s51, m0
	s_mov_b32 m0, s50
	s_nop 0
	global_load_lds_dwordx4 v226, s[48:49]
	s_mov_b32 m0, s51
	s_waitcnt vmcnt(6) lgkmcnt(0)
	s_barrier
	v_lshlrev_b32_e32 v58, 16, v30
	v_and_b32_e32 v59, 0xffff0000, v30
	v_lshlrev_b32_e32 v60, 16, v31
	v_and_b32_e32 v61, 0xffff0000, v31
	v_lshlrev_b32_e32 v30, 16, v18
	v_and_b32_e32 v31, 0xffff0000, v18
	v_lshlrev_b32_e32 v18, 16, v19
	v_and_b32_e32 v19, 0xffff0000, v19
	v_lshlrev_b32_e32 v56, 16, v20
	v_and_b32_e32 v57, 0xffff0000, v20
	v_lshlrev_b32_e32 v62, 16, v32
	v_and_b32_e32 v63, 0xffff0000, v32
	v_lshlrev_b32_e32 v64, 16, v33
	v_and_b32_e32 v65, 0xffff0000, v33
	v_lshlrev_b32_e32 v32, 16, v22
	v_and_b32_e32 v33, 0xffff0000, v22
	v_lshlrev_b32_e32 v22, 16, v23
	v_and_b32_e32 v23, 0xffff0000, v23
	v_lshlrev_b32_e32 v74, 16, v24
	v_and_b32_e32 v75, 0xffff0000, v24
	v_lshlrev_b32_e32 v76, 16, v28
	v_and_b32_e32 v77, 0xffff0000, v28
	v_lshlrev_b32_e32 v24, 16, v25
	v_and_b32_e32 v25, 0xffff0000, v25
	v_lshlrev_b32_e32 v34, 16, v26
	v_and_b32_e32 v35, 0xffff0000, v26
	v_lshlrev_b32_e32 v26, 16, v27
	v_and_b32_e32 v27, 0xffff0000, v27
	s_lshl_b64 s[48:49], s[46:47], 12
	s_or_b32 s46, s46, 1
	s_and_b32 s47, s46, 0xfff
	s_cmp_lg_u32 s47, 1
	v_pk_fma_f32 v[30:31], v[40:41], v[30:31], 0 op_sel_hi:[1,1,0]
	v_pk_fma_f32 v[18:19], v[42:43], v[18:19], 0 op_sel_hi:[1,1,0]
	v_pk_fma_f32 v[40:41], v[44:45], v[56:57], 0 op_sel_hi:[1,1,0]
	v_pk_fma_f32 v[18:19], v[50:51], v[22:23], v[18:19]
	v_pk_fma_f32 v[22:23], v[52:53], v[74:75], v[40:41]
	v_pk_fma_f32 v[30:31], v[48:49], v[32:33], v[30:31]
	v_pk_fma_f32 v[22:23], v[70:71], v[62:63], v[22:23]
	v_pk_fma_f32 v[30:31], v[66:67], v[58:59], v[30:31]
	v_pk_mul_f32 v[22:23], v[22:23], v[76:77]
	v_pk_fma_f32 v[18:19], v[68:69], v[60:61], v[18:19]
	v_cvt_pk_bf16_f32 v20, v22, v23
	v_lshlrev_b32_e32 v22, 16, v21
	v_and_b32_e32 v23, 0xffff0000, v21
	v_pk_fma_f32 v[22:23], v[46:47], v[22:23], 0 op_sel_hi:[1,1,0]
	v_pk_mul_f32 v[30:31], v[30:31], v[34:35]
	v_pk_fma_f32 v[22:23], v[54:55], v[24:25], v[22:23]
	v_lshlrev_b32_e32 v24, 16, v29
	v_pk_fma_f32 v[22:23], v[72:73], v[64:65], v[22:23]
	v_and_b32_e32 v25, 0xffff0000, v29
	v_pk_mul_f32 v[26:27], v[18:19], v[26:27]
	v_pk_mul_f32 v[22:23], v[22:23], v[24:25]
	v_cvt_pk_bf16_f32 v18, v30, v31
	v_cvt_pk_bf16_f32 v19, v26, v27
	v_cvt_pk_bf16_f32 v21, v22, v23
	v_lshl_add_u64 v[44:45], v[204:205], 0, s[48:49]
	global_store_dwordx4 v[44:45], v[18:21], off offset:2048
	global_load_dwordx4 v[18:21], v[192:193], off offset:2048
	s_nop 0
	global_load_dwordx4 v[22:25], v[192:193], off offset:2064
	global_load_dwordx4 v[26:29], v[198:199], off
	global_load_dwordx4 v[30:33], v[198:199], off offset:16
	global_load_dwordx4 v[40:43], v[200:201], off
	global_load_dwordx4 v[50:53], v[200:201], off offset:16
	v_lshlrev_b32_e32 v54, 16, v2
	v_and_b32_e32 v55, 0xffff0000, v2
	v_lshlrev_b32_e32 v2, 16, v3
	v_and_b32_e32 v3, 0xffff0000, v3
	v_lshlrev_b32_e32 v74, 16, v4
	v_and_b32_e32 v75, 0xffff0000, v4
	v_lshlrev_b32_e32 v4, 16, v5
	v_and_b32_e32 v5, 0xffff0000, v5
	v_lshlrev_b32_e32 v56, 16, v6
	v_and_b32_e32 v57, 0xffff0000, v6
	v_lshlrev_b32_e32 v6, 16, v7
	v_and_b32_e32 v7, 0xffff0000, v7
	v_lshlrev_b32_e32 v76, 16, v8
	v_and_b32_e32 v77, 0xffff0000, v8
	v_lshlrev_b32_e32 v8, 16, v9
	v_and_b32_e32 v9, 0xffff0000, v9
	v_lshlrev_b32_e32 v66, 16, v14
	v_and_b32_e32 v67, 0xffff0000, v14
	v_lshlrev_b32_e32 v68, 16, v15
	v_and_b32_e32 v69, 0xffff0000, v15
	v_lshlrev_b32_e32 v70, 16, v16
	v_and_b32_e32 v71, 0xffff0000, v16
	v_lshlrev_b32_e32 v72, 16, v17
	v_and_b32_e32 v73, 0xffff0000, v17
	v_lshlrev_b32_e32 v14, 16, v10
	v_and_b32_e32 v15, 0xffff0000, v10
	v_lshlrev_b32_e32 v10, 16, v11
	v_and_b32_e32 v11, 0xffff0000, v11
	v_lshlrev_b32_e32 v16, 16, v12
	v_and_b32_e32 v17, 0xffff0000, v12
	v_lshlrev_b32_e32 v12, 16, v13
	v_and_b32_e32 v13, 0xffff0000, v13
	v_mov_b32_e32 v34, 0
	v_mov_b32_e32 v46, 0
	v_mov_b32_e32 v47, 0
	v_mov_b32_e32 v48, 0
	s_cselect_b64 s[48:49], -1, 0
	s_cmp_eq_u32 s47, 1
	v_mov_b32_e32 v49, 0
	s_waitcnt vmcnt(5)
	v_pk_fma_f32 v[18:19], v[18:19], v[54:55], 0 op_sel_hi:[1,1,0]
	v_pk_fma_f32 v[2:3], v[20:21], v[2:3], 0 op_sel_hi:[1,1,0]
	s_waitcnt vmcnt(4)
	v_pk_fma_f32 v[20:21], v[22:23], v[74:75], 0 op_sel_hi:[1,1,0]
	v_pk_fma_f32 v[4:5], v[24:25], v[4:5], 0 op_sel_hi:[1,1,0]
	s_waitcnt vmcnt(3)
	v_pk_fma_f32 v[18:19], v[26:27], v[56:57], v[18:19]
	v_pk_fma_f32 v[2:3], v[28:29], v[6:7], v[2:3]
	s_waitcnt vmcnt(2)
	v_pk_fma_f32 v[6:7], v[30:31], v[76:77], v[20:21]
	v_pk_fma_f32 v[4:5], v[32:33], v[8:9], v[4:5]
	s_waitcnt vmcnt(1)
	v_pk_fma_f32 v[8:9], v[40:41], v[66:67], v[18:19]
	v_pk_fma_f32 v[2:3], v[42:43], v[68:69], v[2:3]
	s_waitcnt vmcnt(0)
	v_pk_fma_f32 v[6:7], v[50:51], v[70:71], v[6:7]
	v_pk_fma_f32 v[4:5], v[52:53], v[72:73], v[4:5]
	v_pk_mul_f32 v[8:9], v[8:9], v[14:15]
	v_pk_mul_f32 v[10:11], v[2:3], v[10:11]
	v_pk_mul_f32 v[6:7], v[6:7], v[16:17]
	v_pk_mul_f32 v[12:13], v[4:5], v[12:13]
	v_cvt_pk_bf16_f32 v2, v8, v9
	v_cvt_pk_bf16_f32 v3, v10, v11
	v_cvt_pk_bf16_f32 v4, v6, v7
	v_cvt_pk_bf16_f32 v5, v12, v13
	global_store_dwordx4 v[44:45], v[2:5], off offset:3072
	s_cbranch_scc1 .LBB0_420
	global_load_dwordx4 v[46:49], v[36:37], off offset:-2048

.LBB0_424:
	global_load_dwordx4 v[74:77], v[192:193], off
	global_load_dwordx4 v[78:81], v[192:193], off offset:16
	global_load_dwordx4 v[82:85], v[194:195], off
	global_load_dwordx4 v[86:89], v[194:195], off offset:16
	global_load_dwordx4 v[90:93], v[196:197], off
	global_load_dwordx4 v[94:97], v[196:197], off offset:16
	s_waitcnt vmcnt(0) lgkmcnt(0)
	s_barrier
	s_waitcnt vmcnt(10)
	v_lshlrev_b32_e32 v98, 16, v46
	v_and_b32_e32 v99, 0xffff0000, v46
	v_lshlrev_b32_e32 v46, 16, v47
	v_and_b32_e32 v47, 0xffff0000, v47
	v_lshlrev_b32_e32 v104, 16, v48
	v_and_b32_e32 v105, 0xffff0000, v48
	v_lshlrev_b32_e32 v48, 16, v49
	v_and_b32_e32 v49, 0xffff0000, v49
	s_waitcnt vmcnt(9)
	v_lshlrev_b32_e32 v100, 16, v54
	v_and_b32_e32 v101, 0xffff0000, v54
	v_lshlrev_b32_e32 v54, 16, v55
	v_and_b32_e32 v55, 0xffff0000, v55
	v_lshlrev_b32_e32 v106, 16, v56
	v_and_b32_e32 v107, 0xffff0000, v56
	v_lshlrev_b32_e32 v56, 16, v57
	v_and_b32_e32 v57, 0xffff0000, v57
	s_waitcnt vmcnt(8)
	v_lshlrev_b32_e32 v102, 16, v50
	v_and_b32_e32 v103, 0xffff0000, v50
	v_lshlrev_b32_e32 v50, 16, v51
	v_and_b32_e32 v51, 0xffff0000, v51
	v_lshlrev_b32_e32 v124, 16, v52
	v_and_b32_e32 v125, 0xffff0000, v52
	v_lshlrev_b32_e32 v52, 16, v53
	v_and_b32_e32 v53, 0xffff0000, v53
	s_lshl_b64 s[46:47], s[46:47], 12
	v_lshl_add_u64 v[126:127], v[204:205], 0, s[46:47]
	s_add_u32 s46, s44, 0x60000
	s_addc_u32 s47, s45, 0
	s_cmp_lg_u32 0, -1
	s_cselect_b32 s48, 0, 0
	s_add_i32 s51, s48, s74
	s_add_i32 s74, s51, 0xc000
	s_add_u32 s44, s44, 0x60080
	s_addc_u32 s45, s45, 0
	s_add_i32 s75, s51, 0xe000
	s_add_u32 s48, s42, 0x20000
	s_addc_u32 s49, s43, 0
	s_add_i32 s76, s51, 0x14000
	s_add_u32 s42, s42, 0x20080
	s_addc_u32 s43, s43, 0
	s_add_i32 s51, s51, 0x16000
	s_cmp_lg_u32 s66, 0
	s_waitcnt vmcnt(5)
	v_pk_fma_f32 v[74:75], v[74:75], v[98:99], 0 op_sel_hi:[1,1,0]
	v_pk_fma_f32 v[46:47], v[76:77], v[46:47], 0 op_sel_hi:[1,1,0]
	s_waitcnt vmcnt(4)
	v_pk_fma_f32 v[76:77], v[78:79], v[104:105], 0 op_sel_hi:[1,1,0]
	v_pk_fma_f32 v[48:49], v[80:81], v[48:49], 0 op_sel_hi:[1,1,0]
	s_waitcnt vmcnt(3)
	v_pk_fma_f32 v[58:59], v[82:83], v[58:59], v[74:75]
	v_pk_fma_f32 v[46:47], v[84:85], v[60:61], v[46:47]
	s_waitcnt vmcnt(2)
	v_pk_fma_f32 v[60:61], v[86:87], v[62:63], v[76:77]
	v_pk_fma_f32 v[48:49], v[88:89], v[64:65], v[48:49]
	s_waitcnt vmcnt(1)
	v_pk_fma_f32 v[58:59], v[90:91], v[100:101], v[58:59]
	v_pk_fma_f32 v[46:47], v[92:93], v[54:55], v[46:47]
	s_waitcnt vmcnt(0)
	v_pk_fma_f32 v[54:55], v[94:95], v[106:107], v[60:61]
	v_pk_fma_f32 v[48:49], v[96:97], v[56:57], v[48:49]
	v_pk_mul_f32 v[56:57], v[58:59], v[102:103]
	v_pk_mul_f32 v[50:51], v[46:47], v[50:51]
	v_pk_mul_f32 v[54:55], v[54:55], v[124:125]
	v_pk_mul_f32 v[52:53], v[48:49], v[52:53]
	v_cvt_pk_bf16_f32 v46, v56, v57
	v_cvt_pk_bf16_f32 v47, v50, v51
	v_cvt_pk_bf16_f32 v48, v54, v55
	v_cvt_pk_bf16_f32 v49, v52, v53
	global_store_dwordx4 v[126:127], v[46:49], off offset:2048
	global_load_dwordx4 v[46:49], v[192:193], off offset:2048
	s_nop 0
	global_load_dwordx4 v[50:53], v[192:193], off offset:2064
	global_load_dwordx4 v[54:57], v[198:199], off
	global_load_dwordx4 v[58:61], v[198:199], off offset:16
	global_load_dwordx4 v[62:65], v[200:201], off
	global_load_dwordx4 v[74:77], v[200:201], off offset:16
	v_lshlrev_b32_e32 v78, 16, v34
	v_and_b32_e32 v79, 0xffff0000, v34
	v_lshlrev_b32_e32 v34, 16, v35
	v_and_b32_e32 v35, 0xffff0000, v35
	v_lshlrev_b32_e32 v84, 16, v36
	v_and_b32_e32 v85, 0xffff0000, v36
	v_lshlrev_b32_e32 v36, 16, v37
	v_and_b32_e32 v37, 0xffff0000, v37
	v_lshlrev_b32_e32 v80, 16, v42
	v_and_b32_e32 v81, 0xffff0000, v42
	v_lshlrev_b32_e32 v42, 16, v43
	v_and_b32_e32 v43, 0xffff0000, v43
	v_lshlrev_b32_e32 v86, 16, v44
	v_and_b32_e32 v87, 0xffff0000, v44
	v_lshlrev_b32_e32 v44, 16, v45
	v_and_b32_e32 v45, 0xffff0000, v45
	v_lshlrev_b32_e32 v82, 16, v38
	v_and_b32_e32 v83, 0xffff0000, v38
	v_lshlrev_b32_e32 v38, 16, v39
	v_and_b32_e32 v39, 0xffff0000, v39
	v_lshlrev_b32_e32 v88, 16, v40
	v_and_b32_e32 v89, 0xffff0000, v40
	v_lshlrev_b32_e32 v40, 16, v41
	v_and_b32_e32 v41, 0xffff0000, v41
	s_waitcnt vmcnt(5)
	v_pk_fma_f32 v[46:47], v[46:47], v[78:79], 0 op_sel_hi:[1,1,0]
	v_pk_fma_f32 v[34:35], v[48:49], v[34:35], 0 op_sel_hi:[1,1,0]
	s_waitcnt vmcnt(4)
	v_pk_fma_f32 v[48:49], v[50:51], v[84:85], 0 op_sel_hi:[1,1,0]
	v_pk_fma_f32 v[36:37], v[52:53], v[36:37], 0 op_sel_hi:[1,1,0]
	s_waitcnt vmcnt(3)
	v_pk_fma_f32 v[46:47], v[54:55], v[66:67], v[46:47]
	v_pk_fma_f32 v[34:35], v[56:57], v[68:69], v[34:35]
	s_waitcnt vmcnt(2)
	v_pk_fma_f32 v[48:49], v[58:59], v[70:71], v[48:49]
	v_pk_fma_f32 v[36:37], v[60:61], v[72:73], v[36:37]
	s_waitcnt vmcnt(1)
	v_pk_fma_f32 v[46:47], v[62:63], v[80:81], v[46:47]
	v_pk_fma_f32 v[34:35], v[64:65], v[42:43], v[34:35]
	s_waitcnt vmcnt(0)
	v_pk_fma_f32 v[42:43], v[74:75], v[86:87], v[48:49]
	v_pk_fma_f32 v[36:37], v[76:77], v[44:45], v[36:37]
	v_pk_mul_f32 v[44:45], v[46:47], v[82:83]
	v_pk_mul_f32 v[38:39], v[34:35], v[38:39]
	v_pk_mul_f32 v[42:43], v[42:43], v[88:89]
	v_pk_mul_f32 v[40:41], v[36:37], v[40:41]
	v_cvt_pk_bf16_f32 v34, v44, v45
	v_cvt_pk_bf16_f32 v35, v38, v39
	v_cvt_pk_bf16_f32 v36, v42, v43
	v_cvt_pk_bf16_f32 v37, v40, v41
	global_store_dwordx4 v[126:127], v[34:37], off offset:3072
	s_mov_b32 s77, m0
	s_mov_b32 m0, s74
	s_nop 0
	global_load_lds_dwordx4 v226, s[46:47]
	s_mov_b32 m0, s77
	s_mov_b32 s46, m0
	s_mov_b32 m0, s75
	s_nop 0
	global_load_lds_dwordx4 v226, s[44:45]
	s_mov_b32 m0, s46
	s_mov_b32 s44, m0
	s_mov_b32 m0, s76
	s_nop 0
	global_load_lds_dwordx4 v227, s[48:49]
	s_mov_b32 m0, s44
	s_nop 0
	s_mov_b32 s44, m0
	s_mov_b32 m0, s51
	s_nop 0
	global_load_lds_dwordx4 v227, s[42:43]
	s_mov_b32 m0, s44
	ds_read_b128 v[156:159], v228 offset:16384
	ds_read_b128 v[160:163], v228 offset:18432
	s_cbranch_scc0 .LBB0_473
	s_waitcnt vmcnt(5) lgkmcnt(0)
	s_barrier
	s_cbranch_execnz .LBB0_427
